# RG_SPLIT 8 (one more RG-LRU tile beside the delta prep, one fewer beside the recurrence) with the consumer-loop hoists
# baseline (speedup 1.0000x reference)
; #define RG_RAW_LOAD(tile_) do { _Pragma("unroll") for (int i = 0; i < 5; ++i) { const int q = tid + 512 * i, row = q >> 4, c16 = q & 15, tl = (tile_) * 128 - 3 + row; \
;         pre[i] = (q < 131 * 16 && tl >= 0) ? *(const u32x4*)(XR + ((size_t)b * SEQ + tl) * D + cb0 + c16 * 8) : (u32x4){0u, 0u, 0u, 0u}; } } while (0)
; __device__ __forceinline__ void rglru_task(const Params& P, LAS unsigned char* lds, int b, int n, int qd, int tid, int t0, int t1) {
;     ...
;     const int ntiles = t1;
;     for (int tile = t0; tile < ntiles; ++tile) {
;         const int row0 = prompt ? b * SEQ + tile * 128 : MPR;
;         if (prompt && tile + 1 < ntiles) RG_RAW_LOAD(tile + 1);
.LBB0_1296:
	s_or_b64 exec, exec, s[4:5]
	s_add_i32 s61, s61, 1
	s_cmp_eq_u32 s61, 8
	s_cbranch_scc1 .LBB0_1407
.LBB0_1297:
	s_lshl_b32 s64, s61, 7
	s_cmp_lt_u32 s61, 7
	s_cselect_b64 s[4:5], -1, 0
	s_and_b64 s[68:69], s[58:59], s[4:5]
	s_andn2_b64 vcc, exec, s[68:69]
	s_cbranch_vccnz .LBB0_1309
	s_or_b32 s6, s64, 0x7d
	v_add_u32_e32 v0, s6, v149
	s_waitcnt vmcnt(0)
	v_mov_b32_e32 v50, v68
	v_mov_b32_e32 v51, v68
	v_cmp_lt_i32_e32 vcc, -1, v0
	v_mov_b32_e32 v48, v68
	v_mov_b32_e32 v49, v68
	v_mov_b64_e32 v[54:55], v[50:51]
	s_and_b64 s[52:53], s[10:11], vcc
	v_mov_b64_e32 v[52:53], v[48:49]
	s_and_saveexec_b64 s[4:5], s[52:53]
	s_cbranch_execz .LBB0_1300
	v_mov_b32_e32 v1, v68
	v_lshlrev_b64 v[0:1], 11, v[0:1]
	v_lshl_add_u64 v[0:1], v[74:75], 0, v[0:1]
	global_load_dwordx4 v[52:55], v[0:1], off

; #define RG_RAW_LOAD(tile_) do { _Pragma("unroll") for (int i = 0; i < 5; ++i) { const int q = tid + 512 * i, row = q >> 4, c16 = q & 15, tl = (tile_) * 128 - 3 + row; \
;         pre[i] = (q < 131 * 16 && tl >= 0) ? *(const u32x4*)(XR + ((size_t)b * SEQ + tl) * D + cb0 + c16 * 8) : (u32x4){0u, 0u, 0u, 0u}; } } while (0)
; #define RG_RAW_STORE() do { _Pragma("unroll") for (int i = 0; i < 5; ++i) { const int q = tid + 512 * i; if (q < 131 * 16) *(LAS u32x4*)(rawt + (q >> 4) * 136 + (q & 15) * 8) = pre[i]; } } while (0)
; __device__ __forceinline__ void rglru_task(const Params& P, LAS unsigned char* lds, int b, int n, int qd, int tid, int t0, int t1) {
;     ...
;     if (prompt) { RG_RAW_LOAD(t0); RG_RAW_STORE(); }
.LBB0_1634:
	s_or_b64 exec, exec, s[12:13]
	s_lshl_b64 s[8:9], s[6:7], 22
	s_add_u32 s8, s10, s8
	s_addc_u32 s9, s11, s9
	s_lshl_b32 s10, s18, 1
	v_lshlrev_b32_e32 v2, 3, v0
	s_add_u32 s8, s8, s10
	v_and_b32_e32 v2, 0x78, v2
	s_addc_u32 s9, s9, 0
	v_lshlrev_b32_e32 v48, 1, v2
	v_lshl_add_u64 v[4:5], s[8:9], 0, v[48:49]
	s_mov_b64 s[8:9], 0x5040000
	v_lshl_add_u64 v[74:75], v[4:5], 0, s[8:9]
	v_ashrrev_i32_e32 v79, 4, v0
	s_movk_i32 s8, 0x830
	s_movk_i32 s12, 0xfc82
	v_cmp_gt_i32_e64 s[8:9], s8, v0
	v_cmp_lt_i32_e64 s[10:11], s12, v79
	s_and_b64 s[14:15], s[8:9], s[10:11]
	v_mov_b32_e32 v48, v49
	v_mov_b32_e32 v50, v49
	v_mov_b32_e32 v51, v49
	s_and_saveexec_b64 s[10:11], s[14:15]
	s_cbranch_execz .LBB0_1636
	v_add_u32_e32 v4, 0x3fd, v79
	v_mov_b32_e32 v5, 0
	v_lshlrev_b64 v[4:5], 11, v[4:5]
	v_lshl_add_u64 v[4:5], v[74:75], 0, v[4:5]
	global_load_dwordx4 v[48:51], v[4:5], off
.LBB0_1636:
	s_or_b64 exec, exec, s[10:11]
	v_add_u32_e32 v3, 0x200, v0
	v_mov_b32_e32 v56, 0
	v_ashrrev_i32_e32 v80, 4, v3
	s_movk_i32 s10, 0x630
	v_mov_b32_e32 v57, v56
	v_cmp_gt_i32_e64 s[10:11], s10, v0
	v_cmp_lt_i32_e64 s[12:13], s12, v80
	v_mov_b32_e32 v58, v56
	v_mov_b32_e32 v59, v56
	v_mov_b64_e32 v[52:53], v[56:57]
	s_and_b64 s[14:15], s[10:11], s[12:13]
	v_mov_b64_e32 v[54:55], v[58:59]
	s_and_saveexec_b64 s[12:13], s[14:15]
	s_cbranch_execz .LBB0_1638
	v_add_u32_e32 v4, 0x3fd, v80
	v_mov_b32_e32 v5, v56
	v_lshlrev_b64 v[4:5], 11, v[4:5]
	v_lshl_add_u64 v[4:5], v[74:75], 0, v[4:5]
	global_load_dwordx4 v[52:55], v[4:5], off
.LBB0_1638:
	s_or_b64 exec, exec, s[12:13]
	v_add_u32_e32 v3, 0x400, v0
	v_ashrrev_i32_e32 v81, 4, v3
	s_movk_i32 s12, 0x430
	s_movk_i32 s16, 0xfc82
	v_cmp_gt_i32_e64 s[12:13], s12, v0
	v_cmp_lt_i32_e64 s[14:15], s16, v81
	s_and_b64 s[18:19], s[12:13], s[14:15]
	s_and_saveexec_b64 s[14:15], s[18:19]
	s_cbranch_execz .LBB0_1640
	v_add_u32_e32 v4, 0x3fd, v81
	v_mov_b32_e32 v5, 0
	v_lshlrev_b64 v[4:5], 11, v[4:5]
	v_lshl_add_u64 v[4:5], v[74:75], 0, v[4:5]
	global_load_dwordx4 v[56:59], v[4:5], off
.LBB0_1640:
	s_or_b64 exec, exec, s[14:15]
	v_add_u32_e32 v3, 0x600, v0
	v_mov_b32_e32 v64, 0
	v_ashrrev_i32_e32 v82, 4, v3
	s_movk_i32 s14, 0x230
	v_mov_b32_e32 v65, v64
	v_cmp_gt_i32_e64 s[14:15], s14, v0
	v_cmp_lt_i32_e64 s[16:17], s16, v82
	v_mov_b32_e32 v66, v64
	v_mov_b32_e32 v67, v64
	v_mov_b64_e32 v[60:61], v[64:65]
	s_and_b64 s[18:19], s[14:15], s[16:17]
	v_mov_b64_e32 v[62:63], v[66:67]
	s_and_saveexec_b64 s[16:17], s[18:19]
	s_cbranch_execz .LBB0_1642
	v_add_u32_e32 v4, 0x3fd, v82
	v_mov_b32_e32 v5, 0
	v_lshlrev_b64 v[4:5], 11, v[4:5]
	v_lshl_add_u64 v[4:5], v[74:75], 0, v[4:5]
	global_load_dwordx4 v[60:63], v[4:5], off
.LBB0_1642:
	s_or_b64 exec, exec, s[16:17]
	v_add_u32_e32 v3, 0x800, v0
	v_ashrrev_i32_e32 v83, 4, v3
	s_movk_i32 s18, 0xfc82
	v_cmp_gt_i32_e64 s[16:17], 48, v0
	v_cmp_lt_i32_e64 s[18:19], s18, v83
	s_and_b64 s[20:21], s[16:17], s[18:19]
	v_mov_b32_e32 v65, 0
	v_mov_b32_e32 v66, 0
	v_mov_b32_e32 v67, 0
	s_and_saveexec_b64 s[18:19], s[20:21]
	s_cbranch_execz .LBB0_1644
	v_add_u32_e32 v4, 0x3fd, v83
	v_mov_b32_e32 v5, 0
	v_lshlrev_b64 v[4:5], 11, v[4:5]
	v_lshl_add_u64 v[4:5], v[74:75], 0, v[4:5]
	global_load_dwordx4 v[64:67], v[4:5], off

; __device__ __forceinline__ float softplus_f(float x) { return x > 20.f ? x : log1pf(__expf(x)); }
; #define INP(k) karg_in(k)
; #define RG_RAW_LOAD(tile_) do { _Pragma("unroll") for (int i = 0; i < 5; ++i) { const int q = tid + 512 * i, row = q >> 4, c16 = q & 15, tl = (tile_) * 128 - 3 + row; \
;         pre[i] = (q < 131 * 16 && tl >= 0) ? *(const u32x4*)(XR + ((size_t)b * SEQ + tl) * D + cb0 + c16 * 8) : (u32x4){0u, 0u, 0u, 0u}; } } while (0)
; #define RG_RAW_STORE() do { _Pragma("unroll") for (int i = 0; i < 5; ++i) { const int q = tid + 512 * i; if (q < 131 * 16) *(LAS u32x4*)(rawt + (q >> 4) * 136 + (q & 15) * 8) = pre[i]; } } while (0)
; #define tid opq((wave << 6) | lane_now())
; __device__ __forceinline__ void rglru_task(const Params& P, LAS unsigned char* lds, int b, int n, int qd, int tid, int t0, int t1) {
;     ...
;     const int ch = tid & 31, seg = tid >> 5;
;     const float sp = softplus_f(-INP(21)[oc0 + ch]);
;     float hlast = 0.f;
;     u32x4 pre[5];
;     ...
;     if (prompt) { RG_RAW_LOAD(t0); RG_RAW_STORE(); }
;     __syncthreads();
;     const int ntiles = t1;
;     for (int tile = t0; tile < ntiles; ++tile) {
.LBB0_1651:
	s_or_b64 exec, exec, s[18:19]
	v_lshrrev_b32_e32 v4, 1, v0
	v_and_b32_e32 v10, 0x60, v4
	s_add_i32 s20, 0, 0xc800
	s_lshl_b32 s65, s6, 11
	v_or_b32_e32 v4, v10, v72
	s_add_i32 s57, 0, 0x10800
	v_mov_b32_e32 v5, s20
	s_add_i32 s58, 0, 0x14800
	s_add_i32 s59, 0, 0x15000
	s_add_i32 s63, 0, 0x15800
	s_lshl_b32 s20, s64, 1
	v_mul_u32_u24_e32 v11, 0x110, v4
	v_mov_b32_e32 v4, s57
	v_mov_b32_e32 v68, 0
	s_add_u32 s4, s4, s20
	v_cndmask_b32_e32 v12, v4, v5, vcc
	s_addc_u32 s5, s5, 0
	v_lshlrev_b32_e32 v4, 1, v72
	v_mov_b32_e32 v5, v68
	v_lshlrev_b32_e32 v13, 2, v72
	v_lshl_add_u64 v[4:5], s[4:5], 0, v[4:5]
	s_mov_b64 s[4:5], 0x7080000
	v_lshl_add_u64 v[76:77], v[4:5], 0, s[4:5]
	v_or_b32_e32 v4, 0x80, v13
	v_add_u32_e32 v89, s58, v4
	v_add_u32_e32 v90, s59, v4
	v_or_b32_e32 v4, 0x100, v13
	v_add_u32_e32 v91, s58, v4
	v_add_u32_e32 v92, s59, v4
	v_or_b32_e32 v4, 0x180, v13
	v_add_u32_e32 v93, s58, v4
	v_add_u32_e32 v94, s59, v4
	v_or_b32_e32 v4, 0x200, v13
	v_add_u32_e32 v95, s58, v4
	v_add_u32_e32 v96, s59, v4
	v_or_b32_e32 v4, 0x280, v13
	v_add_u32_e32 v97, s58, v4
	v_add_u32_e32 v98, s59, v4
	v_or_b32_e32 v4, 0x300, v13
	v_add_u32_e32 v99, s58, v4
	v_add_u32_e32 v100, s59, v4
	v_or_b32_e32 v4, 0x380, v13
	v_add_u32_e32 v101, s58, v4
	v_add_u32_e32 v102, s59, v4
	v_or_b32_e32 v4, 0x400, v13
	v_add_u32_e32 v103, s58, v4
	v_add_u32_e32 v104, s59, v4
	v_or_b32_e32 v4, 0x480, v13
	v_add_u32_e32 v105, s58, v4
	v_add_u32_e32 v106, s59, v4
	v_or_b32_e32 v4, 0x500, v13
	v_add_u32_e32 v107, s58, v4
	v_add_u32_e32 v108, s59, v4
	v_or_b32_e32 v4, 0x580, v13
	v_add_u32_e32 v109, s58, v4
	v_add_u32_e32 v110, s59, v4
	v_or_b32_e32 v4, 0x600, v13
	v_ashrrev_i32_e32 v6, 5, v0
	v_add_u32_e32 v111, s58, v4
	v_add_u32_e32 v112, s59, v4
	v_or_b32_e32 v4, 0x680, v13
	v_lshlrev_b32_e32 v85, 3, v6
	v_add_u32_e32 v113, s58, v4
	v_add_u32_e32 v114, s59, v4
	v_or_b32_e32 v4, 0x700, v13
	v_add_u32_e32 v115, s58, v4
	v_add_u32_e32 v116, s59, v4
	v_or_b32_e32 v119, 1, v85
	v_lshl_or_b32 v4, v6, 10, v13
	v_or_b32_e32 v120, 2, v85
	v_add_u32_e32 v126, 0, v4
	v_add_u32_e32 v127, s57, v4
	v_lshl_or_b32 v4, v119, 7, v13
	v_or_b32_e32 v121, 3, v85
	v_add_u32_e32 v128, 0, v4
	v_add_u32_e32 v129, s57, v4
	v_lshl_or_b32 v4, v120, 7, v13
	v_or_b32_e32 v122, 4, v85
	v_add_u32_e32 v130, 0, v4
	v_add_u32_e32 v131, s57, v4
	v_lshl_or_b32 v4, v121, 7, v13
	v_or_b32_e32 v123, 5, v85
	v_add_u32_e32 v132, 0, v4
	v_add_u32_e32 v133, s57, v4
	v_lshl_or_b32 v4, v122, 7, v13
	v_or_b32_e32 v124, 6, v85
	v_add_u32_e32 v134, 0, v4
	v_add_u32_e32 v135, s57, v4
	v_lshl_or_b32 v4, v123, 7, v13
	v_ashrrev_i32_e32 v7, 2, v0
	v_and_b32_e32 v8, 3, v0
	v_lshlrev_b32_e32 v0, 2, v0
	v_or_b32_e32 v125, 7, v85
	v_add_u32_e32 v136, 0, v4
	v_add_u32_e32 v137, s57, v4
	v_lshl_or_b32 v4, v124, 7, v13
	v_add_u32_e32 v86, s58, v0
	v_add_u32_e32 v87, s59, v0
	v_lshlrev_b32_e32 v0, 9, v1
	v_add_u32_e32 v138, 0, v4
	v_add_u32_e32 v139, s57, v4
	v_lshl_or_b32 v4, v125, 7, v13
	v_lshl_add_u32 v3, v3, 1, 0
	v_mul_lo_u32 v9, v7, s54
	v_cmp_eq_u32_e64 s[20:21], 15, v6
	v_lshlrev_b32_e32 v1, 7, v10
	v_add3_u32 v0, v12, v13, v0
	v_cmp_lt_i32_e64 s[22:23], 0, v6
	v_cmp_lt_i32_e64 s[24:25], 1, v6
	v_cmp_lt_i32_e64 s[26:27], 2, v6
	v_cmp_lt_i32_e64 s[28:29], 3, v6
	v_cmp_lt_i32_e64 s[30:31], 4, v6
	v_cmp_lt_i32_e64 s[34:35], 5, v6
	v_cmp_lt_i32_e64 s[36:37], 6, v6
	v_cmp_lt_i32_e64 s[38:39], 7, v6
	v_cmp_lt_i32_e64 s[40:41], 8, v6
	v_cmp_lt_i32_e64 s[42:43], 9, v6
	v_cmp_lt_i32_e64 s[44:45], 10, v6
	v_cmp_lt_i32_e64 s[46:47], 11, v6
	v_cmp_lt_i32_e64 s[48:49], 12, v6
	v_cmp_lt_i32_e64 s[50:51], 13, v6
	v_cmp_lt_i32_e64 s[52:53], 14, v6
	v_add_u32_e32 v140, 0, v4
	v_add_u32_e32 v141, s57, v4
	v_mul_lo_u32 v4, v79, s54
	v_mul_lo_u32 v5, v80, s54
	v_mul_lo_u32 v6, v81, s54
	v_mul_lo_u32 v10, v82, s54
	v_mov_b32_e32 v12, 0x8800
	v_cmp_eq_u32_e64 s[18:19], s3, v8
	v_add_u32_e32 v88, s63, v13
	s_mov_b32 s68, 8
	v_add_u32_e32 v117, s59, v13
	v_add_u32_e32 v118, s58, v13
	v_lshlrev_b32_e32 v142, 7, v8
	v_lshl_add_u32 v143, v7, 7, v12
	v_lshl_add_u32 v144, v8, 6, v9
	v_add_u32_e32 v145, v3, v11
	v_add_u32_e32 v146, v0, v1
	v_mov_b32_e32 v147, 0x3c088889
	s_mov_b32 s66, 0xbe99999a
	v_add_u32_e32 v148, v2, v4
	v_add_u32_e32 v149, v2, v5
	v_add_u32_e32 v150, v2, v6
	v_add_u32_e32 v151, v2, v10
	s_waitcnt lgkmcnt(0)
	s_barrier
	s_branch .LBB0_1653

; #define RG_RAW_LOAD(tile_) do { _Pragma("unroll") for (int i = 0; i < 5; ++i) { const int q = tid + 512 * i, row = q >> 4, c16 = q & 15, tl = (tile_) * 128 - 3 + row; \
;         pre[i] = (q < 131 * 16 && tl >= 0) ? *(const u32x4*)(XR + ((size_t)b * SEQ + tl) * D + cb0 + c16 * 8) : (u32x4){0u, 0u, 0u, 0u}; } } while (0)
; #define RG_RAW_STORE() do { _Pragma("unroll") for (int i = 0; i < 5; ++i) { const int q = tid + 512 * i; if (q < 131 * 16) *(LAS u32x4*)(rawt + (q >> 4) * 136 + (q & 15) * 8) = pre[i]; } } while (0)
; __device__ __forceinline__ void rglru_task(const Params& P, LAS unsigned char* lds, int b, int n, int qd, int tid, int t0, int t1) {
;     ...
;     if (prompt) { RG_RAW_LOAD(t0); RG_RAW_STORE(); }
.LBB0_1706:
	s_or_b64 exec, exec, s[14:15]
	s_lshl_b32 s7, s56, 17
	s_add_u32 s7, s10, s7
	s_addc_u32 s10, s11, 0
	s_lshl_b64 s[8:9], s[12:13], 1
	v_lshlrev_b32_e32 v2, 3, v0
	s_add_u32 s8, s7, s8
	v_and_b32_e32 v2, 0x78, v2
	s_addc_u32 s9, s10, s9
	v_lshlrev_b32_e32 v48, 1, v2
	v_lshl_add_u64 v[4:5], s[8:9], 0, v[48:49]
	s_mov_b64 s[8:9], 0x5040000
	s_movk_i32 s7, 0x830
	v_lshl_add_u64 v[74:75], v[4:5], 0, s[8:9]
	v_ashrrev_i32_e32 v79, 4, v0
	v_cmp_gt_i32_e64 s[8:9], s7, v0
	s_movk_i32 s7, 0xfc82
	v_cmp_lt_i32_e64 s[10:11], s7, v79
	s_and_b64 s[12:13], s[8:9], s[10:11]
	v_mov_b32_e32 v48, v49
	v_mov_b32_e32 v50, v49
	v_mov_b32_e32 v51, v49
	s_and_saveexec_b64 s[10:11], s[12:13]
	s_cbranch_execz .LBB0_1708
	v_add_u32_e32 v4, 0x3fd, v79
	v_mov_b32_e32 v5, 0
	v_lshlrev_b64 v[4:5], 11, v[4:5]
	v_lshl_add_u64 v[4:5], v[74:75], 0, v[4:5]
	global_load_dwordx4 v[48:51], v[4:5], off
.LBB0_1708:
	s_or_b64 exec, exec, s[10:11]
	v_add_u32_e32 v3, 0x200, v0
	v_mov_b32_e32 v56, 0
	v_ashrrev_i32_e32 v80, 4, v3
	s_movk_i32 s10, 0x630
	v_mov_b32_e32 v57, v56
	v_cmp_gt_i32_e64 s[10:11], s10, v0
	v_cmp_lt_i32_e64 s[12:13], s7, v80
	v_mov_b32_e32 v58, v56
	v_mov_b32_e32 v59, v56
	v_mov_b64_e32 v[52:53], v[56:57]
	s_and_b64 s[14:15], s[10:11], s[12:13]
	v_mov_b64_e32 v[54:55], v[58:59]
	s_and_saveexec_b64 s[12:13], s[14:15]
	s_cbranch_execz .LBB0_1710
	v_add_u32_e32 v4, 0x3fd, v80
	v_mov_b32_e32 v5, v56
	v_lshlrev_b64 v[4:5], 11, v[4:5]
	v_lshl_add_u64 v[4:5], v[74:75], 0, v[4:5]
	global_load_dwordx4 v[52:55], v[4:5], off
.LBB0_1710:
	s_or_b64 exec, exec, s[12:13]
	v_add_u32_e32 v3, 0x400, v0
	s_movk_i32 s7, 0x430
	v_ashrrev_i32_e32 v81, 4, v3
	v_cmp_gt_i32_e64 s[12:13], s7, v0
	s_movk_i32 s7, 0xfc82
	v_cmp_lt_i32_e64 s[14:15], s7, v81
	s_and_b64 s[16:17], s[12:13], s[14:15]
	s_and_saveexec_b64 s[14:15], s[16:17]
	s_cbranch_execz .LBB0_1712
	v_add_u32_e32 v4, 0x3fd, v81
	v_mov_b32_e32 v5, 0
	v_lshlrev_b64 v[4:5], 11, v[4:5]
	v_lshl_add_u64 v[4:5], v[74:75], 0, v[4:5]
	global_load_dwordx4 v[56:59], v[4:5], off
.LBB0_1712:
	s_or_b64 exec, exec, s[14:15]
	v_add_u32_e32 v3, 0x600, v0
	v_mov_b32_e32 v64, 0
	v_ashrrev_i32_e32 v82, 4, v3
	s_movk_i32 s14, 0x230
	v_mov_b32_e32 v65, v64
	v_cmp_gt_i32_e64 s[14:15], s14, v0
	v_cmp_lt_i32_e64 s[16:17], s7, v82
	v_mov_b32_e32 v66, v64
	v_mov_b32_e32 v67, v64
	v_mov_b64_e32 v[60:61], v[64:65]
	s_and_b64 s[18:19], s[14:15], s[16:17]
	v_mov_b64_e32 v[62:63], v[66:67]
	s_and_saveexec_b64 s[16:17], s[18:19]
	s_cbranch_execz .LBB0_1714
	v_add_u32_e32 v4, 0x3fd, v82
	v_mov_b32_e32 v5, 0
	v_lshlrev_b64 v[4:5], 11, v[4:5]
	v_lshl_add_u64 v[4:5], v[74:75], 0, v[4:5]
	global_load_dwordx4 v[60:63], v[4:5], off

; __device__ __forceinline__ float softplus_f(float x) { return x > 20.f ? x : log1pf(__expf(x)); }
; #define INP(k) karg_in(k)
; #define RG_RAW_LOAD(tile_) do { _Pragma("unroll") for (int i = 0; i < 5; ++i) { const int q = tid + 512 * i, row = q >> 4, c16 = q & 15, tl = (tile_) * 128 - 3 + row; \
;         pre[i] = (q < 131 * 16 && tl >= 0) ? *(const u32x4*)(XR + ((size_t)b * SEQ + tl) * D + cb0 + c16 * 8) : (u32x4){0u, 0u, 0u, 0u}; } } while (0)
; #define RG_RAW_STORE() do { _Pragma("unroll") for (int i = 0; i < 5; ++i) { const int q = tid + 512 * i; if (q < 131 * 16) *(LAS u32x4*)(rawt + (q >> 4) * 136 + (q & 15) * 8) = pre[i]; } } while (0)
; #define tid opq((wave << 6) | lane_now())
; __device__ __forceinline__ void rglru_task(const Params& P, LAS unsigned char* lds, int b, int n, int qd, int tid, int t0, int t1) {
;     ...
;     const int ch = tid & 31, seg = tid >> 5;
;     const float sp = softplus_f(-INP(21)[oc0 + ch]);
;     float hlast = 0.f;
;     u32x4 pre[5];
;     ...
;     if (prompt) { RG_RAW_LOAD(t0); RG_RAW_STORE(); }
;     __syncthreads();
;     const int ntiles = t1;
;     for (int tile = t0; tile < ntiles; ++tile) {
.LBB0_1722:
	s_or_b64 exec, exec, s[18:19]
	v_lshrrev_b32_e32 v4, 1, v0
	s_mov_b32 s7, 0
	v_and_b32_e32 v8, 3, v0
	v_and_b32_e32 v10, 0x60, v4
	s_lshl_b32 s61, s56, 6
	v_cmp_eq_u32_e64 s[18:19], s3, v8
	v_or_b32_e32 v4, v10, v72
	s_add_i32 s3, 0, 0xc800
	s_lshl_b64 s[20:21], s[6:7], 1
	v_mul_u32_u24_e32 v11, 0x110, v4
	v_mov_b32_e32 v4, s57
	v_mov_b32_e32 v5, s3
	v_mov_b32_e32 v68, 0
	s_add_u32 s4, s4, s20
	v_cndmask_b32_e32 v12, v4, v5, vcc
	s_addc_u32 s5, s5, s21
	v_lshlrev_b32_e32 v4, 1, v72
	v_mov_b32_e32 v5, v68
	v_lshlrev_b32_e32 v13, 2, v72
	v_lshl_add_u64 v[4:5], s[4:5], 0, v[4:5]
	s_mov_b64 s[4:5], 0x7080000
	v_lshl_add_u64 v[76:77], v[4:5], 0, s[4:5]
	v_or_b32_e32 v4, 0x80, v13
	v_add_u32_e32 v89, s58, v4
	v_add_u32_e32 v90, s59, v4
	v_or_b32_e32 v4, 0x100, v13
	v_add_u32_e32 v91, s58, v4
	v_add_u32_e32 v92, s59, v4
	v_or_b32_e32 v4, 0x180, v13
	v_add_u32_e32 v93, s58, v4
	v_add_u32_e32 v94, s59, v4
	v_or_b32_e32 v4, 0x200, v13
	v_add_u32_e32 v95, s58, v4
	v_add_u32_e32 v96, s59, v4
	v_or_b32_e32 v4, 0x280, v13
	v_add_u32_e32 v97, s58, v4
	v_add_u32_e32 v98, s59, v4
	v_or_b32_e32 v4, 0x300, v13
	v_add_u32_e32 v99, s58, v4
	v_add_u32_e32 v100, s59, v4
	v_or_b32_e32 v4, 0x380, v13
	v_add_u32_e32 v101, s58, v4
	v_add_u32_e32 v102, s59, v4
	v_or_b32_e32 v4, 0x400, v13
	v_add_u32_e32 v103, s58, v4
	v_add_u32_e32 v104, s59, v4
	v_or_b32_e32 v4, 0x480, v13
	v_add_u32_e32 v105, s58, v4
	v_add_u32_e32 v106, s59, v4
	v_or_b32_e32 v4, 0x500, v13
	v_add_u32_e32 v107, s58, v4
	v_add_u32_e32 v108, s59, v4
	v_or_b32_e32 v4, 0x580, v13
	v_add_u32_e32 v109, s58, v4
	v_add_u32_e32 v110, s59, v4
	v_or_b32_e32 v4, 0x600, v13
	v_ashrrev_i32_e32 v6, 5, v0
	v_add_u32_e32 v111, s58, v4
	v_add_u32_e32 v112, s59, v4
	v_or_b32_e32 v4, 0x680, v13
	v_lshlrev_b32_e32 v85, 3, v6
	v_add_u32_e32 v113, s58, v4
	v_add_u32_e32 v114, s59, v4
	v_or_b32_e32 v4, 0x700, v13
	v_add_u32_e32 v115, s58, v4
	v_add_u32_e32 v116, s59, v4
	v_or_b32_e32 v119, 1, v85
	v_lshl_or_b32 v4, v6, 10, v13
	v_or_b32_e32 v120, 2, v85
	v_add_u32_e32 v126, 0, v4
	v_add_u32_e32 v127, s57, v4
	v_lshl_or_b32 v4, v119, 7, v13
	v_or_b32_e32 v121, 3, v85
	v_add_u32_e32 v128, 0, v4
	v_add_u32_e32 v129, s57, v4
	v_lshl_or_b32 v4, v120, 7, v13
	v_or_b32_e32 v122, 4, v85
	v_add_u32_e32 v130, 0, v4
	v_add_u32_e32 v131, s57, v4
	v_lshl_or_b32 v4, v121, 7, v13
	v_or_b32_e32 v123, 5, v85
	v_add_u32_e32 v132, 0, v4
	v_add_u32_e32 v133, s57, v4
	v_lshl_or_b32 v4, v122, 7, v13
	v_or_b32_e32 v124, 6, v85
	v_add_u32_e32 v134, 0, v4
	v_add_u32_e32 v135, s57, v4
	v_lshl_or_b32 v4, v123, 7, v13
	v_ashrrev_i32_e32 v7, 2, v0
	v_lshlrev_b32_e32 v0, 2, v0
	v_or_b32_e32 v125, 7, v85
	v_add_u32_e32 v136, 0, v4
	v_add_u32_e32 v137, s57, v4
	v_lshl_or_b32 v4, v124, 7, v13
	v_add_u32_e32 v86, s58, v0
	v_add_u32_e32 v87, s59, v0
	v_lshlrev_b32_e32 v0, 9, v1
	v_add_u32_e32 v138, 0, v4
	v_add_u32_e32 v139, s57, v4
	v_lshl_or_b32 v4, v125, 7, v13
	v_lshl_add_u32 v3, v3, 1, 0
	v_mul_lo_u32 v9, v7, s54
	v_cmp_eq_u32_e64 s[20:21], 15, v6
	v_lshlrev_b32_e32 v1, 7, v10
	v_add3_u32 v0, v12, v13, v0
	v_cmp_lt_i32_e64 s[22:23], 0, v6
	v_cmp_lt_i32_e64 s[24:25], 1, v6
	v_cmp_lt_i32_e64 s[26:27], 2, v6
	v_cmp_lt_i32_e64 s[28:29], 3, v6
	v_cmp_lt_i32_e64 s[30:31], 4, v6
	v_cmp_lt_i32_e64 s[34:35], 5, v6
	v_cmp_lt_i32_e64 s[36:37], 6, v6
	v_cmp_lt_i32_e64 s[38:39], 7, v6
	v_cmp_lt_i32_e64 s[40:41], 8, v6
	v_cmp_lt_i32_e64 s[42:43], 9, v6
	v_cmp_lt_i32_e64 s[44:45], 10, v6
	v_cmp_lt_i32_e64 s[46:47], 11, v6
	v_cmp_lt_i32_e64 s[48:49], 12, v6
	v_cmp_lt_i32_e64 s[50:51], 13, v6
	v_cmp_lt_i32_e64 s[52:53], 14, v6
	v_add_u32_e32 v140, 0, v4
	v_add_u32_e32 v141, s57, v4
	v_mul_lo_u32 v4, v79, s54
	v_mul_lo_u32 v5, v80, s54
	v_mul_lo_u32 v6, v81, s54
	v_mul_lo_u32 v10, v82, s54
	v_mov_b32_e32 v12, 0x8800
	v_add_u32_e32 v88, s63, v13
	s_mov_b32 s65, 8
	v_add_u32_e32 v117, s59, v13
	v_add_u32_e32 v118, s58, v13
	v_lshlrev_b32_e32 v142, 7, v8
	v_lshl_add_u32 v143, v7, 7, v12
	v_lshl_add_u32 v144, v8, 6, v9
	v_add_u32_e32 v145, v3, v11
	v_add_u32_e32 v146, v0, v1
	v_mov_b32_e32 v147, 0x3c088889
	s_mov_b32 s3, 0xbe99999a
	v_add_u32_e32 v148, v2, v4
	v_add_u32_e32 v149, v2, v5
	v_add_u32_e32 v150, v2, v6
	v_add_u32_e32 v151, v2, v10
	s_waitcnt lgkmcnt(0)
	s_barrier
	s_branch .LBB0_1724

.LBB0_1879:
	v_add_u32_e32 v4, 0x3fd, v83
	v_mov_b32_e32 v5, 0
	v_lshlrev_b64 v[4:5], 11, v[4:5]
	v_lshl_add_u64 v[4:5], v[74:75], 0, v[4:5]
	global_load_dwordx4 v[64:67], v[4:5], off
	s_or_b64 exec, exec, s[18:19]
	v_lshl_add_u32 v2, v2, 1, s62
	s_and_saveexec_b64 s[18:19], s[8:9]
	s_cbranch_execz .LBB0_1716
